# MLA V^T LDS tile: rows with bit 3 set shifted 8 B inside the row pad to remove the 2-way bank conflict of the ds_read2_b64 PV fragment reads
# speedup vs baseline: 1.0023x; 1.0023x over previous
; template <int DK, bool SB> ...
;     ...
;   u32x4 rk[NKL], rv[2];
;   unsigned offK[NKL], offV[2];
; #pragma unroll
;   for (int i = 0; i < NKL; i++) { int c = tid + 256 * i; int row = c / KCH, ch = c - row * KCH; offK[i] = (unsigned)((row * kstride + ch * 8) * 2); }
; #pragma unroll
;   for (int i = 0; i < 2; i++) { int c = tid + 256 * i; int row = c >> 3, ch = c & 7; offV[i] = (unsigned)((row * vstride + ch * 8) * 2); }
;   auto prefetch = [&](int kt) {
;     const char* kb_ = (const char*)(Kp + (size_t)kt * 64 * kstride);
;     const char* vb_ = (const char*)(Vtp + kt * 64);
; #pragma unroll
;     for (int i = 0; i < NKL; i++) rk[i] = *(const u32x4*)(kb_ + offK[i]);
; #pragma unroll
;     for (int i = 0; i < 2; i++) rv[i] = *(const u32x4*)(vb_ + offV[i]);
;   };
;   auto lds_store = [&](int bsel) {
;     u16* wK = sbase + bsel * BUFE; u16* wV = wK + 64 * KSTR;
; #pragma unroll
;     for (int i = 0; i < NKL; i++) { int c = tid + 256 * i; int row = c / KCH, ch = c - row * KCH; *(u32x4*)(wK + row * KSTR + ch * 8) = rk[i]; }
; #pragma unroll
;     for (int i = 0; i < 2; i++) { int c = tid + 256 * i; int row = c >> 3, ch = c & 7; *(u32x4*)(wV + row * 72 + ch * 8) = rv[i]; }
;   };
;   prefetch(SB ? ntiles - 1 : 0);
;   __syncthreads();
;   lds_store(0);
;   { int nx = SB ? ntiles - 2 : 1; if (ntiles < 2) nx = SB ? ntiles - 1 : 0; prefetch(nx); }
;   __syncthreads();
.LBB0_800:
	s_mov_b32 s93, s47
	s_and_b32 s54, s50, 7
	s_lshl_b64 s[2:3], s[92:93], 9
	s_mov_b32 s95, s47
	s_cmp_lg_u32 s4, 0
	s_mov_b32 s91, s47
	s_cbranch_scc0 .LBB0_812
	s_mul_i32 s5, s92, 0x600
	v_readlane_b32 s6, v254, 41
	s_mul_hi_u32 s4, s92, 0x600
	v_readlane_b32 s7, v254, 42
	s_add_u32 s5, s6, s5
	s_addc_u32 s6, s7, s4
	s_mul_i32 s7, s54, 0xc0
	s_add_u32 s4, s5, s7
	s_addc_u32 s5, s6, 0
	s_mul_i32 s8, s90, 0x600
	v_readlane_b32 s10, v254, 50
	s_mul_hi_u32 s6, s90, 0x600
	v_readlane_b32 s11, v254, 51
	s_add_u32 s8, s10, s8
	s_addc_u32 s6, s11, s6
	s_add_u32 s86, s8, s7
	v_mov_b32_e32 v20, v160
	s_mov_b64 s[38:39], s[56:57]
	s_addc_u32 s87, s6, 0
	s_lshl_b64 s[6:7], s[94:95], 1
	s_add_u32 s80, s38, s6
	v_mul_hi_i32 v0, v20, s29
	v_ashrrev_i32_e32 v30, 1, v20
	s_movk_i32 s6, 0xffe0
	v_lshrrev_b32_e32 v1, 31, v0
	v_ashrrev_i32_e32 v0, 1, v0
	v_bfe_u32 v21, v20, 5, 1
	v_bfi_b32 v108, s6, v30, v20
	v_add_u32_e32 v32, v0, v1
	s_mov_b32 s6, 0xffffff4
	v_mov_b64_e32 v[22:23], s[4:5]
	v_mad_u64_u32 v[24:25], s[4:5], v32, s6, v[20:21]
	v_mul_lo_u32 v0, v32, s33
	v_add_u32_e32 v12, 0x100, v20
	v_lshl_add_u32 v162, v24, 4, v0
	v_mul_hi_i32 v0, v12, s29
	v_lshrrev_b32_e32 v1, 31, v0
	v_ashrrev_i32_e32 v0, 1, v0
	s_waitcnt vmcnt(7)
	v_add_u32_e32 v8, 0x200, v20
	v_add_u32_e32 v25, v0, v1
	v_mul_hi_i32 v4, v8, s29
	v_cmp_gt_i32_e32 vcc, s67, v108
	v_mad_u64_u32 v[26:27], s[4:5], v25, s6, v[12:13]
	v_lshrrev_b32_e32 v5, 31, v4
	v_ashrrev_i32_e32 v4, 1, v4
	v_cndmask_b32_e32 v31, 0, v108, vcc
	v_mul_lo_u32 v0, v25, s33
	v_add_u32_e32 v27, v4, v5
	v_lshl_add_u32 v110, v26, 4, v0
	global_load_dwordx4 v[0:3], v162, s[86:87]
	v_mad_u64_u32 v[28:29], s[4:5], v27, s6, v[8:9]
	v_mad_i64_i32 v[22:23], s[4:5], v31, s33, v[22:23]
	s_addc_u32 s81, s39, s7
	s_add_i32 s4, s67, s88
	s_add_i32 s4, s4, -1
	s_lshr_b32 s4, s4, 6
	s_add_i32 s6, s51, 63
	global_load_dwordx4 v[4:7], v110, s[86:87]
	s_add_i32 s5, s4, 1
	s_lshr_b32 s6, s6, 6
	v_mul_lo_u32 v8, v27, s33
	s_cmp_lt_u32 s4, s6
	v_lshl_add_u32 v112, v28, 4, v8
	v_lshlrev_b32_e32 v8, 3, v20
	v_ashrrev_i32_e32 v33, 3, v20
	s_cselect_b32 s55, s5, s6
	v_and_b32_e32 v29, 56, v8
	v_mul_lo_u32 v13, v33, s51
	v_ashrrev_i32_e32 v34, 3, v12
	s_cmp_gt_u32 s55, 1
	global_load_dwordx4 v[8:11], v112, s[86:87]
	v_add_lshl_u32 v114, v13, v29, 1
	v_mul_lo_u32 v16, v34, s51
	v_lshlrev_b32_e32 v118, 4, v21
	v_mov_b32_e32 v119, v163
	s_cselect_b32 s4, 0x18000, 0
	global_load_dwordx4 v[12:15], v114, s[80:81]
	v_add_lshl_u32 v116, v16, v29, 1
	v_lshl_add_u64 v[22:23], v[22:23], 0, v[118:119]
	s_cselect_b32 s6, 0x80, 0
	s_add_u32 s4, s86, s4
	global_load_dwordx4 v[16:19], v116, s[80:81]
	global_load_dwordx4 v[64:67], v[22:23], off
	global_load_dwordx4 v[68:71], v[22:23], off offset:32
	global_load_dwordx4 v[72:75], v[22:23], off offset:64
	global_load_dwordx4 v[76:79], v[22:23], off offset:96
	global_load_dwordx4 v[80:83], v[22:23], off offset:128
	global_load_dwordx4 v[84:87], v[22:23], off offset:160
	s_addc_u32 s5, s87, 0
	s_add_u32 s6, s80, s6
	s_barrier
	global_load_dwordx4 v[88:91], v110, s[4:5]
	s_addc_u32 s7, s81, 0
	global_load_dwordx4 v[92:95], v112, s[4:5]
	global_load_dwordx4 v[100:103], v114, s[6:7]
	global_load_dwordx4 v[96:99], v162, s[4:5]
	global_load_dwordx4 v[104:107], v116, s[6:7]
	v_and_b32_e32 v22, 0xffffffe0, v30
	v_lshlrev_b32_e32 v30, 28, v32
	v_sub_u32_e32 v24, v24, v30
	s_movk_i32 s6, 0x68
	v_mul_lo_u32 v109, v32, s6
	v_lshlrev_b32_e32 v32, 3, v24
	v_lshlrev_b32_e32 v24, 4, v24
	v_lshl_add_u32 v24, v109, 1, v24
	v_mul_lo_u32 v120, v25, s6
	v_mul_lo_u32 v121, v27, s6
	v_mul_lo_u32 v122, v33, s44
	v_lshlrev_b32_e32 v123, 1, v29
	v_bfe_u32 v240, v160, 6, 1
	v_lshl_add_u32 v123, v240, 3, v123
	v_mul_lo_u32 v125, v34, s44
	v_and_b32_e32 v20, 31, v20
	v_lshlrev_b32_e32 v23, 3, v21
	v_cmp_gt_i32_e64 s[4:5], s67, v22
	v_lshlrev_b32_e32 v119, 2, v21
	v_mul_u32_u24_e32 v127, 0xd0, v20
	v_sub_u32_e32 v128, 0, v23
	v_mov_b32_e32 v21, v163
	v_mov_b32_e32 v23, v163
	v_mov_b32_e32 v29, v163
	v_mov_b32_e32 v30, v163
	v_mov_b32_e32 v31, v163
	s_mov_b32 s46, 0
	v_mov_b32_e32 v111, v163
	v_mov_b32_e32 v113, v163
	v_mov_b32_e32 v115, v163
	v_mov_b32_e32 v117, v163
	v_mov_b32_e32 v124, 0
	s_waitcnt vmcnt(22)
	v_mov_b32_e32 v135, 0xf149f2ca
	s_mov_b32 s42, 64
	s_waitcnt vmcnt(21)
	v_lshlrev_b32_e32 v130, 1, v32
	s_waitcnt vmcnt(15)
	ds_write_b128 v24, v[0:3]
	v_lshlrev_b32_e32 v0, 28, v25
	v_sub_u32_e32 v0, v26, v0
	v_lshlrev_b32_e32 v1, 3, v0
	v_lshlrev_b32_e32 v0, 4, v0
	v_lshl_add_u32 v0, v120, 1, v0
	v_mov_b32_e32 v24, v163
	v_mov_b32_e32 v25, v163
	v_mov_b32_e32 v26, v163
	v_lshlrev_b32_e32 v131, 1, v1
	s_waitcnt vmcnt(14)
	ds_write_b128 v0, v[4:7]
	v_lshlrev_b32_e32 v0, 28, v27
	v_sub_u32_e32 v0, v28, v0
	v_lshlrev_b32_e32 v2, 3, v0
	v_lshlrev_b32_e32 v0, 4, v0
	v_lshl_add_u32 v0, v121, 1, v0
	v_mov_b32_e32 v27, v163
	v_mov_b32_e32 v28, v163
	v_lshlrev_b32_e32 v132, 1, v2
	s_waitcnt vmcnt(13)
	ds_write_b128 v0, v[8:11]
	v_lshl_add_u32 v0, v122, 1, v123
	s_waitcnt vmcnt(12)
	ds_write_b64 v0, v[12:13] offset:13312
	ds_write_b64 v0, v[14:15] offset:13320
	v_lshl_add_u32 v0, v125, 1, v123
	s_waitcnt vmcnt(11)
	ds_write_b64 v0, v[16:17] offset:13312
	ds_write_b64 v0, v[18:19] offset:13320
	v_add_u32_e32 v0, s88, v22
	v_ashrrev_i32_e32 v126, 6, v0
	v_mul_u32_u24_e32 v0, 0x48, v20
	v_mov_b32_e32 v16, v163
	v_mov_b32_e32 v17, v163
	v_mov_b32_e32 v18, v163
	v_mov_b32_e32 v19, v163
	v_mov_b32_e32 v20, v163
	v_mov_b32_e32 v22, v163
	v_lshlrev_b32_e32 v129, 1, v0
	v_and_b32_e32 v0, 8, v194
	v_add_u32_e32 v129, v129, v0
	v_mov_b64_e32 v[0:1], v[16:17]
	v_mov_b64_e32 v[2:3], v[18:19]
	v_mov_b64_e32 v[4:5], v[20:21]
	v_mov_b64_e32 v[6:7], v[22:23]
	v_mov_b64_e32 v[8:9], v[24:25]
	v_mov_b64_e32 v[10:11], v[26:27]
	v_mov_b64_e32 v[12:13], v[28:29]
	v_mov_b64_e32 v[14:15], v[30:31]
	s_waitcnt lgkmcnt(0)
	s_barrier
	v_cmp_le_i32_e64 s[6:7], s46, v126
	s_and_b64 s[6:7], s[4:5], s[6:7]
	s_and_saveexec_b64 s[52:53], s[6:7]
	s_cbranch_execz .LBB0_805

; template <int DK, bool SB> ...
;     ...
;   auto prefetch = [&](int kt) {
;     const char* kb_ = (const char*)(Kp + (size_t)kt * 64 * kstride);
;     const char* vb_ = (const char*)(Vtp + kt * 64);
; #pragma unroll
;     for (int i = 0; i < NKL; i++) rk[i] = *(const u32x4*)(kb_ + offK[i]);
; #pragma unroll
;     for (int i = 0; i < 2; i++) rv[i] = *(const u32x4*)(vb_ + offV[i]);
;   };
;   auto lds_store = [&](int bsel) {
;     u16* wK = sbase + bsel * BUFE; u16* wV = wK + 64 * KSTR;
; #pragma unroll
;     for (int i = 0; i < NKL; i++) { int c = tid + 256 * i; int row = c / KCH, ch = c - row * KCH; *(u32x4*)(wK + row * KSTR + ch * 8) = rk[i]; }
; #pragma unroll
;     for (int i = 0; i < 2; i++) { int c = tid + 256 * i; int row = c >> 3, ch = c & 7; *(u32x4*)(wV + row * 72 + ch * 8) = rv[i]; }
;   };
;     ...
;     if (it + 1 < ntiles) {
;       lds_store((it + 1) & 1);
;       int nx = SB ? kt - 2 : kt + 2; if (it + 2 >= ntiles) nx = kt; prefetch(nx);
.LBB0_805:
	s_or_b64 exec, exec, s[52:53]
	s_add_i32 s6, s46, 1
	s_cmp_ge_u32 s6, s55
	s_cbranch_scc1 .LBB0_807
	s_bitcmp1_b32 s6, 0
	s_cselect_b32 s7, 0x5800, 0
	v_lshlrev_b32_e32 v32, 1, v109
	v_add3_u32 v32, s7, v32, v130
	s_waitcnt vmcnt(1)
	ds_write_b128 v32, v[96:99]
	v_lshlrev_b32_e32 v32, 1, v120
	v_add3_u32 v32, s7, v32, v131
	ds_write_b128 v32, v[88:91]
	v_lshlrev_b32_e32 v32, 1, v121
	v_add3_u32 v32, s7, v32, v132
	ds_write_b128 v32, v[92:95]
	v_lshlrev_b32_e32 v32, 1, v122
	v_add3_u32 v32, s7, v32, v123
	ds_write_b64 v32, v[100:101] offset:13312
	ds_write_b64 v32, v[102:103] offset:13320
	v_lshlrev_b32_e32 v32, 1, v125
	v_add3_u32 v32, s7, v32, v123
	s_add_i32 s7, s46, 2
	s_cmp_lt_u32 s7, s55
	s_cselect_b32 s7, s7, s46
	s_mul_i32 s8, s7, 0x18000
	s_mul_hi_u32 s9, s7, 0x18000
	s_add_u32 s8, s86, s8
	s_addc_u32 s9, s87, s9
	s_waitcnt vmcnt(0)
	ds_write_b64 v32, v[104:105] offset:13312
	ds_write_b64 v32, v[106:107] offset:13320
	s_lshl_b32 s46, s7, 6
	v_lshl_add_u64 v[32:33], s[8:9], 0, v[162:163]
	v_lshl_add_u64 v[34:35], s[8:9], 0, v[110:111]
	global_load_dwordx4 v[96:99], v[32:33], off
	global_load_dwordx4 v[88:91], v[34:35], off
	v_lshl_add_u64 v[32:33], s[8:9], 0, v[112:113]
	s_lshl_b64 s[8:9], s[46:47], 1
	s_add_u32 s8, s80, s8
	s_addc_u32 s9, s81, s9
	v_lshl_add_u64 v[34:35], s[8:9], 0, v[114:115]
	global_load_dwordx4 v[92:95], v[32:33], off
	global_load_dwordx4 v[100:103], v[34:35], off
	v_lshl_add_u64 v[32:33], s[8:9], 0, v[116:117]
	global_load_dwordx4 v[104:107], v[32:33], off
